# v28 + weight-copy loop: spurious vmcnt(0) in the no-gain branch removed so the next item's loads stay in flight during the LDS transpose
# baseline (speedup 1.0000x reference)
.LBB0_162:
	s_andn2_saveexec_b64 s[44:45], s[44:45]
	s_cbranch_execz .LBB0_164
	v_mov_b32_e32 v208, 1.0
	v_mov_b32_e32 v209, v208
	v_mov_b32_e32 v206, v208
	v_mov_b32_e32 v210, v208
	v_mov_b32_e32 v202, v208
	v_mov_b32_e32 v204, v208
	v_mov_b32_e32 v198, v208
	v_mov_b32_e32 v200, v208
	v_mov_b32_e32 v194, v208
	v_mov_b32_e32 v196, v208
	v_mov_b32_e32 v190, v208
	v_mov_b32_e32 v192, v208
	v_mov_b32_e32 v186, v208
	v_mov_b32_e32 v188, v208
	v_mov_b32_e32 v184, v208
	v_mov_b32_e32 v185, v208

.LBB0_325:
	s_andn2_saveexec_b64 s[40:41], s[40:41]
	s_cbranch_execz .LBB0_327
	v_mov_b32_e32 v208, 1.0
	v_mov_b32_e32 v209, v208
	v_mov_b32_e32 v206, v208
	v_mov_b32_e32 v210, v208
	v_mov_b32_e32 v202, v208
	v_mov_b32_e32 v204, v208
	v_mov_b32_e32 v198, v208
	v_mov_b32_e32 v200, v208
	v_mov_b32_e32 v194, v208
	v_mov_b32_e32 v196, v208
	v_mov_b32_e32 v190, v208
	v_mov_b32_e32 v192, v208
	v_mov_b32_e32 v186, v208
	v_mov_b32_e32 v188, v208
	v_mov_b32_e32 v184, v208
	v_mov_b32_e32 v185, v208

.LBB0_661:
	s_andn2_saveexec_b64 s[4:5], s[4:5]
	s_cbranch_execz .LBB0_663
	v_mov_b32_e32 v208, 1.0
	v_mov_b32_e32 v209, v208
	v_mov_b32_e32 v206, v208
	v_mov_b32_e32 v210, v208
	v_mov_b32_e32 v202, v208
	v_mov_b32_e32 v204, v208
	v_mov_b32_e32 v198, v208
	v_mov_b32_e32 v200, v208
	v_mov_b32_e32 v194, v208
	v_mov_b32_e32 v196, v208
	v_mov_b32_e32 v190, v208
	v_mov_b32_e32 v192, v208
	v_mov_b32_e32 v186, v208
	v_mov_b32_e32 v188, v208
	v_mov_b32_e32 v184, v208
	v_mov_b32_e32 v185, v208
